# LoRA GEMM call 3 unit order mirrored across workgroup halves (bx^128) so every workgroup runs 3 LoRA units instead of 4 or 2
# baseline (speedup 1.0000x reference)
;     __host__ __device__ bool next(int i, Unit& u) const {
;         const long L = (long)i * G + c; if (L >= nwg) return false;
;         int wgid = (int)L; { const int q = nwg / NXCD, r = nwg % NXCD, xcd = wgid % NXCD, off = wgid / NXCD; wgid = (xcd < r ? xcd * (q + 1) : r * (q + 1) + (xcd - r) * q) + off; }
;         const int nig = WGM * nN, gid = wgid / nig, fm = gid * WGM, gsz = (nM - fm) < WGM ? (nM - fm) : WGM;
;         u.pm = fm + ((wgid % nig) % gsz); u.pn = (wgid % nig) / gsz; return true;
; template <class Epi, class Sched, bool ALIGN_EPI = false>
; __device__ __forceinline__ void gemm_phase(PG8_LAS unsigned char* lds, const Gemm g, const Sched& S, const Epi& E) {
;     int tid_ = threadIdx.x; asm volatile("" : "+v"(tid_));
;     const int tid = tid_, wid = __builtin_amdgcn_readfirstlane(tid >> 6), lane = tid & 63, wr = wid >> 2, wc = wid & 3, fr = lane & 15, fq = lane >> 4;
;     const int K = g.K, nt = K / BK;
;     unsigned voffA[2], voffB[2];
; #pragma unroll
;     for (int i = 0; i < 2; ++i) { int R, C; stage_rc(tid * 16 + i * 8192, R, C); const int Rb = Epi::PERM ? ((R & ~31) + perm32(R & 31)) : R;
;         voffA[i] = (unsigned)(R * g.lda + C) * 2u; voffB[i] = (unsigned)(Rb * g.ldb + C) * 2u; }
;     const size_t kstep = (size_t)(BK * 2);
;     const size_t hstepA = (size_t)HALF * g.lda * 2, hstepB = (size_t)HALF * g.ldb * 2;
;     const size_t tstepA = 2 * hstepA, tstepB = 2 * hstepB;
;     const unsigned ldsw = (unsigned)wid * 1024u;
;     const int aoff = lds_byte(wr * 64 + fr, fq * 8), boff = lds_byte(wc * 32 + fr, fq * 8);
;     ...
;     Unit cur, nxt; int ui = 0;
;     if (!S.next(0, cur)) return;
;     f32x4 acc[2][2][4][2];
; #pragma unroll
;     for (int a = 0; a < 2; ++a)
; #pragma unroll
;         for (int b = 0; b < 2; ++b)
; #pragma unroll
;             for (int m = 0; m < 4; ++m)
; #pragma unroll
;                 for (int n = 0; n < 2; ++n) acc[a][b][m][n] = (f32x4){0.f, 0.f, 0.f, 0.f};
;     bf16x8 At[4][2], B0[2][2], B1[2][2];
;     const char* cA = (const char*)g.A + (size_t)cur.pm * tstepA; const char* cB = (const char*)g.Bt + (size_t)cur.pn * tstepB;
;     S.a_ready(cur);
;     PG8_STAGE(PG8_SB(0, 0), cB, voffB); PG8_STAGE(PG8_SB(0, 1), cB + hstepB, voffB); PG8_STAGE(PG8_SA(0, 0), cA, voffA); PG8_STAGE(PG8_SA(0, 1), cA + hstepA, voffA);
;     if (wr == 1) PG8_BAR;
;     PG8_WAIT_V(2); PG8_BAR;
.LBB0_1199:
	s_movk_i32 s2, 0x200
	s_xor_b32 s99, s33, 0x80
	v_mov_b32_e32 v1, v0
	s_andn2_b64 vcc, exec, s[12:13]
	v_readfirstlane_b32 s5, v1
	s_cbranch_vccnz .LBB0_1218
	v_lshlrev_b32_e32 v2, 4, v1
	v_add_u32_e32 v3, 0x2000, v2
	v_ashrrev_i32_e32 v4, 31, v3
	v_lshrrev_b32_e32 v4, 22, v4
	v_add_u32_e32 v4, v3, v4
	v_ashrrev_i32_e32 v14, 10, v4
	v_mul_i32_i24_e32 v4, 0x400, v14
	v_sub_u32_e32 v3, v3, v4
	v_lshrrev_b32_e32 v4, 4, v3
	v_bitop3_b32 v3, v4, v3, 32 bitop3:0x6c
	v_ashrrev_i32_e32 v4, 31, v3
	v_lshrrev_b32_e32 v4, 26, v4
	v_add_u32_e32 v4, v3, v4
	v_lshlrev_b32_e32 v5, 3, v14
	v_ashrrev_i32_e32 v15, 6, v4
	v_and_b32_e32 v5, -16, v5
	v_add_u32_e32 v5, v15, v5
	v_and_b32_e32 v6, 3, v15
	s_mov_b32 s4, 0x7fffffe0
	v_lshrrev_b32_e32 v7, 2, v5
	v_lshlrev_b32_e32 v8, 1, v5
	v_and_b32_e32 v4, 0xc0, v4
	v_and_or_b32 v6, v5, s4, v6
	v_and_b32_e32 v7, 4, v7
	v_and_b32_e32 v8, 24, v8
	v_sub_u32_e32 v3, v3, v4
	v_mov_b32_e32 v4, 1
	v_or3_b32 v6, v6, v7, v8
	v_lshlrev_b32_e32 v7, 5, v14
	v_ashrrev_i16_sdwa v3, v4, sext(v3) dst_sel:DWORD dst_unused:UNUSED_PAD src0_sel:DWORD src1_sel:BYTE_0
	v_and_b32_e32 v7, 32, v7
	v_bfe_i32 v16, v3, 0, 16
	v_mul_lo_u32 v6, v6, s2
	v_add_u32_e32 v3, v7, v16
	v_lshlrev_b32_e32 v5, 11, v5
	v_add_lshl_u32 v130, v6, v3, 1
	v_lshl_add_u32 v132, v3, 1, v5
	v_bfe_i32 v3, v1, 27, 1
	v_lshrrev_b32_e32 v3, 22, v3
	v_add_u32_e32 v3, v2, v3
	v_and_b32_e32 v3, 0xfffffc00, v3
	v_sub_u32_e32 v2, v2, v3
	s_ashr_i32 s6, s5, 6
	s_ashr_i32 s3, s2, 31
	v_lshrrev_b32_e32 v3, 4, v2
	v_ashrrev_i32_e32 v5, 31, v1
	s_ashr_i32 s7, s5, 8
	s_lshl_b64 s[12:13], s[2:3], 8
	s_lshl_b64 s[14:15], s[2:3], 9
	s_lshl_b32 s0, s6, 10
	v_bitop3_b32 v2, v3, v2, 32 bitop3:0x6c
	v_lshrrev_b32_e32 v5, 26, v5
	s_add_u32 s1, s56, 0xb7900400
	v_ashrrev_i32_e32 v3, 31, v2
	v_add_u32_e32 v5, v1, v5
	s_addc_u32 s36, s57, 0
	v_lshrrev_b32_e32 v3, 26, v3
	v_ashrrev_i32_e32 v18, 6, v5
	s_add_u32 s37, s56, 0xce80000
	v_add_u32_e32 v3, v2, v3
	v_lshlrev_b32_e32 v5, 3, v18
	s_addc_u32 s38, s57, 0
	v_ashrrev_i32_e32 v17, 6, v3
	v_and_b32_e32 v5, -16, v5
	v_add_u32_e32 v5, v17, v5
	v_and_b32_e32 v6, 3, v17
	s_and_b64 s[10:11], s[10:11], exec
	v_and_or_b32 v6, v5, s4, v6
	s_cselect_b32 s4, 49, 48
	s_mul_i32 s4, s53, s4
	s_xor_b32 s98, s52, 16
	s_add_i32 s4, s4, s98
	s_mul_hi_i32 s10, s4, 0x2aaaaaab
	s_lshr_b32 s11, s10, 31
	s_ashr_i32 s10, s10, 4
	s_add_i32 s10, s10, s11
	s_lshl_b32 s11, s10, 3
	s_mulk_i32 s10, 0x60
	s_sub_i32 s10, s4, s10
	s_bfe_i32 s4, s10, 0x80000
	s_bfe_u32 s4, s4, 0x3000c
	s_add_i32 s16, s10, s4
	s_bfe_i32 s4, s16, 0x80000
	s_sext_i32_i16 s18, s4
	s_lshr_b32 s4, s18, 3
	s_and_b32 s16, s16, 0xf8
	s_sub_i32 s10, s10, s16
	s_bfe_i64 s[16:17], s[4:5], 0x100000
	s_ashr_i32 s18, s18, 3
	s_sext_i32_i8 s10, s10
	s_mul_hi_u32 s16, s14, s18
	s_mul_i32 s17, s14, s17
	v_lshrrev_b32_e32 v7, 2, v5
	v_lshlrev_b32_e32 v8, 1, v5
	v_and_b32_e32 v3, 0xc0, v3
	s_add_i32 s22, s11, s10
	s_add_i32 s19, s16, s17
	s_lshr_b64 s[16:17], s[2:3], 23
	v_and_b32_e32 v7, 4, v7
	v_and_b32_e32 v8, 24, v8
	v_sub_u32_e32 v2, v2, v3
	s_ashr_i32 s23, s22, 31
	s_mul_i32 s16, s16, s18
	v_or3_b32 v6, v6, v7, v8
	v_lshlrev_b32_e32 v7, 5, v18
	v_ashrrev_i16_sdwa v2, v4, sext(v2) dst_sel:DWORD dst_unused:UNUSED_PAD src0_sel:DWORD src1_sel:BYTE_0
	s_lshl_b64 s[10:11], s[22:23], 19
	s_add_i32 s19, s19, s16
	s_mul_i32 s16, s14, s18
	v_and_b32_e32 v7, 32, v7
	v_bfe_i32 v19, v2, 0, 16
	s_add_u32 s30, s37, s16
	v_mul_lo_u32 v6, v6, s2
	v_add_u32_e32 v2, v7, v19
	s_addc_u32 s31, s38, s19
	s_add_i32 s23, s0, 0
	v_add_lshl_u32 v134, v6, v2, 1
	s_add_i32 m0, s23, 0x10000
	v_lshlrev_b32_e32 v3, 11, v5
	global_load_lds_dwordx4 v134, s[30:31]
	s_add_i32 m0, s23, 0x12000
	s_add_u32 s16, s30, s12
	global_load_lds_dwordx4 v130, s[30:31]
	s_addc_u32 s17, s31, s13
	s_add_i32 m0, s23, 0x14000
	v_lshl_add_u32 v136, v2, 1, v3
	global_load_lds_dwordx4 v134, s[16:17]
	s_add_i32 m0, s23, 0x16000
	s_add_u32 s34, s1, s10
	s_addc_u32 s35, s36, s11
	s_add_i32 s39, s23, 0x2000
	global_load_lds_dwordx4 v130, s[16:17]
	s_mov_b32 m0, s23
	s_add_u32 s10, s34, 0x40000
	global_load_lds_dwordx4 v136, s[34:35]
	s_mov_b32 m0, s39
	s_addc_u32 s11, s35, 0
	s_add_i32 s40, s23, 0x4000
	global_load_lds_dwordx4 v132, s[34:35]
	s_mov_b32 m0, s40
	s_add_i32 s41, s23, 0x6000
	global_load_lds_dwordx4 v136, s[10:11]
	s_mov_b32 m0, s41
	v_mov_b32_e32 v135, 0
	global_load_lds_dwordx4 v132, s[10:11]
	v_mov_b32_e32 v131, v135
	v_mov_b32_e32 v137, v135
	v_mov_b32_e32 v133, v135
	s_cmp_eq_u32 s7, 1
	s_mov_b32 s42, 0
	v_lshl_add_u64 v[10:11], s[30:31], 0, v[134:135]
	v_lshl_add_u64 v[6:7], s[30:31], 0, v[130:131]
	v_lshl_add_u64 v[4:5], s[16:17], 0, v[134:135]
	v_lshl_add_u64 v[2:3], s[16:17], 0, v[130:131]
	v_lshl_add_u64 v[8:9], s[34:35], 0, v[136:137]
	s_cselect_b64 s[10:11], -1, 0
	s_cmp_lg_u32 s7, 1
	v_lshl_add_u64 v[12:13], s[34:35], 0, v[132:133]
	s_cbranch_scc1 .LBB0_1202
	s_barrier

;     __host__ __device__ bool next(int i, Unit& u) const {
;         const long L = (long)i * G + c; if (L >= nwg) return false;
;         int wgid = (int)L; { const int q = nwg / NXCD, r = nwg % NXCD, xcd = wgid % NXCD, off = wgid / NXCD; wgid = (xcd < r ? xcd * (q + 1) : r * (q + 1) + (xcd - r) * q) + off; }
;         const int nig = WGM * nN, gid = wgid / nig, fm = gid * WGM, gsz = (nM - fm) < WGM ? (nM - fm) : WGM;
;         u.pm = fm + ((wgid % nig) % gsz); u.pn = (wgid % nig) / gsz; return true;
; template <class Epi, class Sched, bool ALIGN_EPI = false>
; __device__ __forceinline__ void gemm_phase(PG8_LAS unsigned char* lds, const Gemm g, const Sched& S, const Epi& E) {
;     ...
;         const bool has_next = S.next(ui + 1, nxt);
.LBB0_1205:
	s_add_i32 s42, s42, 1
	s_mul_i32 s4, s42, s50
	s_mul_hi_u32 s5, s42, s86
	s_add_i32 s5, s5, s4
	s_mul_i32 s4, s42, s86
	s_add_u32 s4, s4, s99
	s_addc_u32 s5, s5, s51
	v_cmp_gt_i64_e32 vcc, s[4:5], v[144:145]
	v_cmp_lt_i64_e64 s[6:7], s[4:5], v[142:143]
	s_cbranch_vccnz .LBB0_1207
	s_ashr_i32 s5, s4, 31
	s_lshr_b32 s5, s5, 29
	s_add_i32 s5, s4, s5
	s_ashr_i32 s24, s5, 3
	s_and_b32 s5, s5, -8
	s_sub_i32 s4, s4, s5
	s_cmp_lt_i32 s4, 0
	s_cselect_b32 s5, 49, 48
	s_mul_i32 s4, s4, s5
	s_add_i32 s4, s4, s24
	s_mul_hi_i32 s5, s4, 0x2aaaaaab
	s_lshr_b32 s24, s5, 31
	s_ashr_i32 s5, s5, 4
	s_add_i32 s5, s5, s24
	s_lshl_b32 s24, s5, 3
	s_sub_i32 s25, 32, s24
	s_min_i32 s25, s25, 8
	s_abs_i32 s26, s25
	v_cvt_f32_u32_e32 v2, s26
	s_sub_i32 s28, 0, s26
	s_mulk_i32 s5, 0x60
	s_sub_i32 s4, s4, s5
	v_rcp_iflag_f32_e32 v2, v2
	s_abs_i32 s5, s4
	s_xor_b32 s27, s4, s25
	s_ashr_i32 s27, s27, 31
	v_mul_f32_e32 v2, 0x4f7ffffe, v2
	v_cvt_u32_f32_e32 v2, v2
	s_nop 0
	v_readfirstlane_b32 s29, v2
	s_mul_i32 s28, s28, s29
	s_mul_hi_u32 s28, s29, s28
	s_add_i32 s29, s29, s28
	s_mul_hi_u32 s28, s5, s29
	s_mul_i32 s29, s28, s26
	s_sub_i32 s5, s5, s29
	s_add_i32 s52, s28, 1
	s_sub_i32 s29, s5, s26
	s_cmp_ge_u32 s5, s26
	s_cselect_b32 s28, s52, s28
	s_cselect_b32 s5, s29, s5
	s_add_i32 s29, s28, 1
	s_cmp_ge_u32 s5, s26
	s_cselect_b32 s5, s29, s28
	s_xor_b32 s5, s5, s27
	s_sub_i32 s52, s5, s27
	s_mul_i32 s5, s52, s25
	s_sub_i32 s4, s4, s5
	s_add_i32 s24, s24, s4
